# GEMM K-loop compute segments without the s_setprio 1/0 toggles
# speedup vs baseline: 1.0024x; 1.0024x over previous
.LBB0_110:
	s_add_i32 s39, s10, 2
	s_add_u32 s40, s8, 0x80
	s_addc_u32 s11, s9, 0
	s_add_i32 s42, 0, 0x10000
	s_cmp_eq_u32 s82, s10
	s_cselect_b32 s11, s3, s11
	s_cselect_b32 s10, s2, s40
	v_add_u32_e32 v0, s42, v190
	s_cselect_b32 s41, s1, s38
	s_cselect_b32 s40, s0, s36
	s_add_i32 s43, 0, 0x14000
	ds_read_b128 v[130:133], v0
	ds_read_b128 v[134:137], v0 offset:1024
	ds_read_b128 v[138:141], v0 offset:2048
	ds_read_b128 v[142:145], v0 offset:3072
	v_add_u32_e32 v0, s43, v190
	ds_read_b128 v[146:149], v0
	ds_read_b128 v[162:165], v0 offset:1024
	ds_read_b128 v[166:169], v0 offset:2048
	ds_read_b128 v[192:195], v0 offset:3072
	v_lshl_add_u64 v[170:171], s[8:9], 0, v[158:159]
	s_add_i32 m0, s75, 0xc000
	ds_read_b128 v[196:199], v191
	ds_read_b128 v[200:203], v191 offset:1024
	ds_read_b128 v[204:207], v191 offset:2048
	ds_read_b128 v[208:211], v191 offset:3072
	ds_read_b128 v[212:215], v191 offset:4096
	ds_read_b128 v[216:219], v191 offset:5120
	ds_read_b128 v[220:223], v191 offset:6144
	ds_read_b128 v[224:227], v191 offset:7168
	global_load_lds_dwordx4 v[170:171], off
	v_lshl_add_u64 v[170:171], s[8:9], 0, v[160:161]
	s_add_i32 m0, s75, 0xe000
	s_nop 0
	global_load_lds_dwordx4 v[170:171], off
	s_waitcnt vmcnt(8)
	s_waitcnt lgkmcnt(0)
	s_barrier
	v_mfma_f32_16x16x32_bf16 v[126:129], v[130:133], v[196:199], v[126:129]
	v_mfma_f32_16x16x32_bf16 v[122:125], v[138:141], v[196:199], v[122:125]
	v_mfma_f32_16x16x32_bf16 v[110:113], v[130:133], v[204:207], v[110:113]
	v_mfma_f32_16x16x32_bf16 v[106:109], v[138:141], v[204:207], v[106:109]
	v_mfma_f32_16x16x32_bf16 v[94:97], v[130:133], v[212:215], v[94:97]
	v_mfma_f32_16x16x32_bf16 v[90:93], v[138:141], v[212:215], v[90:93]
	v_mfma_f32_16x16x32_bf16 v[78:81], v[130:133], v[220:223], v[78:81]
	v_mfma_f32_16x16x32_bf16 v[74:77], v[138:141], v[220:223], v[74:77]
	v_mfma_f32_16x16x32_bf16 v[126:129], v[134:137], v[200:203], v[126:129]
	v_mfma_f32_16x16x32_bf16 v[122:125], v[142:145], v[200:203], v[122:125]
	v_mfma_f32_16x16x32_bf16 v[110:113], v[134:137], v[208:211], v[110:113]
	v_mfma_f32_16x16x32_bf16 v[106:109], v[142:145], v[208:211], v[106:109]
	v_mfma_f32_16x16x32_bf16 v[94:97], v[134:137], v[216:219], v[94:97]
	v_mfma_f32_16x16x32_bf16 v[90:93], v[142:145], v[216:219], v[90:93]
	v_mfma_f32_16x16x32_bf16 v[78:81], v[134:137], v[224:227], v[78:81]
	v_mfma_f32_16x16x32_bf16 v[74:77], v[142:145], v[224:227], v[74:77]
	v_mfma_f32_16x16x32_bf16 v[118:121], v[146:149], v[196:199], v[118:121]
	v_mfma_f32_16x16x32_bf16 v[114:117], v[166:169], v[196:199], v[114:117]
	v_mfma_f32_16x16x32_bf16 v[102:105], v[146:149], v[204:207], v[102:105]
	v_mfma_f32_16x16x32_bf16 v[98:101], v[166:169], v[204:207], v[98:101]
	v_mfma_f32_16x16x32_bf16 v[86:89], v[146:149], v[212:215], v[86:89]
	v_mfma_f32_16x16x32_bf16 v[82:85], v[166:169], v[212:215], v[82:85]
	v_mfma_f32_16x16x32_bf16 v[70:73], v[146:149], v[220:223], v[70:73]
	v_mfma_f32_16x16x32_bf16 v[66:69], v[166:169], v[220:223], v[66:69]
	v_mfma_f32_16x16x32_bf16 v[118:121], v[162:165], v[200:203], v[118:121]
	v_mfma_f32_16x16x32_bf16 v[114:117], v[192:195], v[200:203], v[114:117]
	v_mfma_f32_16x16x32_bf16 v[102:105], v[162:165], v[208:211], v[102:105]
	v_mfma_f32_16x16x32_bf16 v[98:101], v[192:195], v[208:211], v[98:101]
	v_mfma_f32_16x16x32_bf16 v[86:89], v[162:165], v[216:219], v[86:89]
	v_mfma_f32_16x16x32_bf16 v[82:85], v[192:195], v[216:219], v[82:85]
	v_mfma_f32_16x16x32_bf16 v[70:73], v[162:165], v[224:227], v[70:73]
	v_mfma_f32_16x16x32_bf16 v[66:69], v[192:195], v[224:227], v[66:69]
	s_barrier
	s_add_i32 s42, s42, s74
	v_lshl_add_u64 v[170:171], s[40:41], 0, v[152:153]
	s_mov_b32 m0, s42
	ds_read_b128 v[196:199], v191 offset:16384
	ds_read_b128 v[200:203], v191 offset:17408
	ds_read_b128 v[204:207], v191 offset:18432
	ds_read_b128 v[208:211], v191 offset:19456
	ds_read_b128 v[212:215], v191 offset:20480
	ds_read_b128 v[216:219], v191 offset:21504
	ds_read_b128 v[220:223], v191 offset:22528
	ds_read_b128 v[224:227], v191 offset:23552
	global_load_lds_dwordx4 v[170:171], off
	s_add_i32 m0, s42, 0x2000
	v_lshl_add_u64 v[228:229], s[40:41], 0, v[156:157]
	s_add_u32 s40, s40, s20
	s_addc_u32 s41, s41, s21
	s_add_i32 s42, s43, s74
	global_load_lds_dwordx4 v[228:229], off
	v_lshl_add_u64 v[230:231], s[40:41], 0, v[152:153]
	s_mov_b32 m0, s42
	v_lshl_add_u64 v[232:233], s[40:41], 0, v[156:157]
	global_load_lds_dwordx4 v[230:231], off
	s_add_i32 m0, s42, 0x2000
	v_lshl_add_u64 v[234:235], s[10:11], 0, v[150:151]
	global_load_lds_dwordx4 v[232:233], off
	s_mov_b32 m0, s75
	v_lshl_add_u64 v[236:237], s[10:11], 0, v[154:155]
	global_load_lds_dwordx4 v[234:235], off
	s_mov_b32 m0, s71
	s_nop 0
	global_load_lds_dwordx4 v[236:237], off
	s_waitcnt vmcnt(8)
	s_waitcnt lgkmcnt(0)
	s_barrier
	v_mfma_f32_16x16x32_bf16 v[62:65], v[130:133], v[196:199], v[62:65]
	v_mfma_f32_16x16x32_bf16 v[58:61], v[138:141], v[196:199], v[58:61]
	v_mfma_f32_16x16x32_bf16 v[46:49], v[130:133], v[204:207], v[46:49]
	v_mfma_f32_16x16x32_bf16 v[42:45], v[138:141], v[204:207], v[42:45]
	v_mfma_f32_16x16x32_bf16 v[30:33], v[130:133], v[212:215], v[30:33]
	v_mfma_f32_16x16x32_bf16 v[26:29], v[138:141], v[212:215], v[26:29]
	v_mfma_f32_16x16x32_bf16 v[14:17], v[130:133], v[220:223], v[14:17]
	v_mfma_f32_16x16x32_bf16 v[10:13], v[138:141], v[220:223], v[10:13]
	v_mfma_f32_16x16x32_bf16 v[62:65], v[134:137], v[200:203], v[62:65]
	v_mfma_f32_16x16x32_bf16 v[58:61], v[142:145], v[200:203], v[58:61]
	v_mfma_f32_16x16x32_bf16 v[46:49], v[134:137], v[208:211], v[46:49]
	v_mfma_f32_16x16x32_bf16 v[42:45], v[142:145], v[208:211], v[42:45]
	v_mfma_f32_16x16x32_bf16 v[30:33], v[134:137], v[216:219], v[30:33]
	v_mfma_f32_16x16x32_bf16 v[26:29], v[142:145], v[216:219], v[26:29]
	v_mfma_f32_16x16x32_bf16 v[14:17], v[134:137], v[224:227], v[14:17]
	v_mfma_f32_16x16x32_bf16 v[10:13], v[142:145], v[224:227], v[10:13]
	v_mfma_f32_16x16x32_bf16 v[54:57], v[146:149], v[196:199], v[54:57]
	v_mfma_f32_16x16x32_bf16 v[50:53], v[166:169], v[196:199], v[50:53]
	v_mfma_f32_16x16x32_bf16 v[38:41], v[146:149], v[204:207], v[38:41]
	v_mfma_f32_16x16x32_bf16 v[34:37], v[166:169], v[204:207], v[34:37]
	v_mfma_f32_16x16x32_bf16 v[22:25], v[146:149], v[212:215], v[22:25]
	v_mfma_f32_16x16x32_bf16 v[18:21], v[166:169], v[212:215], v[18:21]
	v_mfma_f32_16x16x32_bf16 v[6:9], v[146:149], v[220:223], v[6:9]
	v_mfma_f32_16x16x32_bf16 v[2:5], v[166:169], v[220:223], v[2:5]
	v_mfma_f32_16x16x32_bf16 v[54:57], v[162:165], v[200:203], v[54:57]
	v_mfma_f32_16x16x32_bf16 v[50:53], v[192:195], v[200:203], v[50:53]
	v_mfma_f32_16x16x32_bf16 v[38:41], v[162:165], v[208:211], v[38:41]
	v_mfma_f32_16x16x32_bf16 v[34:37], v[192:195], v[208:211], v[34:37]
	v_mfma_f32_16x16x32_bf16 v[22:25], v[162:165], v[216:219], v[22:25]
	v_mfma_f32_16x16x32_bf16 v[18:21], v[192:195], v[216:219], v[18:21]
	v_mfma_f32_16x16x32_bf16 v[6:9], v[162:165], v[224:227], v[6:9]
	v_mfma_f32_16x16x32_bf16 v[2:5], v[192:195], v[224:227], v[2:5]
	s_barrier
	s_add_i32 s40, 0, 0x18000
	v_add_u32_e32 v0, s40, v190
	s_add_i32 s41, 0, 0x1c000
	ds_read_b128 v[130:133], v0
	ds_read_b128 v[134:137], v0 offset:1024
	ds_read_b128 v[138:141], v0 offset:2048
	ds_read_b128 v[142:145], v0 offset:3072
	v_add_u32_e32 v0, s41, v190
	ds_read_b128 v[146:149], v0
	ds_read_b128 v[162:165], v0 offset:1024
	ds_read_b128 v[166:169], v0 offset:2048
	ds_read_b128 v[192:195], v0 offset:3072
	s_add_u32 s10, s10, s18
	s_addc_u32 s11, s11, s19
	s_mov_b32 m0, s89
	v_lshl_add_u64 v[238:239], s[10:11], 0, v[150:151]
	ds_read_b128 v[196:199], v191 offset:32768
	ds_read_b128 v[200:203], v191 offset:33792
	ds_read_b128 v[204:207], v191 offset:34816
	ds_read_b128 v[208:211], v191 offset:35840
	ds_read_b128 v[212:215], v191 offset:36864
	ds_read_b128 v[216:219], v191 offset:37888
	ds_read_b128 v[220:223], v191 offset:38912
	ds_read_b128 v[224:227], v191 offset:39936
	global_load_lds_dwordx4 v[238:239], off
	v_lshl_add_u64 v[238:239], s[10:11], 0, v[154:155]
	s_mov_b32 m0, s79
	s_nop 0
	global_load_lds_dwordx4 v[238:239], off
	s_waitcnt vmcnt(8)
	s_waitcnt lgkmcnt(0)
	s_barrier
	v_mfma_f32_16x16x32_bf16 v[126:129], v[130:133], v[196:199], v[126:129]
	v_mfma_f32_16x16x32_bf16 v[122:125], v[138:141], v[196:199], v[122:125]
	v_mfma_f32_16x16x32_bf16 v[110:113], v[130:133], v[204:207], v[110:113]
	v_mfma_f32_16x16x32_bf16 v[106:109], v[138:141], v[204:207], v[106:109]
	v_mfma_f32_16x16x32_bf16 v[94:97], v[130:133], v[212:215], v[94:97]
	v_mfma_f32_16x16x32_bf16 v[90:93], v[138:141], v[212:215], v[90:93]
	v_mfma_f32_16x16x32_bf16 v[78:81], v[130:133], v[220:223], v[78:81]
	v_mfma_f32_16x16x32_bf16 v[74:77], v[138:141], v[220:223], v[74:77]
	v_mfma_f32_16x16x32_bf16 v[126:129], v[134:137], v[200:203], v[126:129]
	v_mfma_f32_16x16x32_bf16 v[122:125], v[142:145], v[200:203], v[122:125]
	v_mfma_f32_16x16x32_bf16 v[110:113], v[134:137], v[208:211], v[110:113]
	v_mfma_f32_16x16x32_bf16 v[106:109], v[142:145], v[208:211], v[106:109]
	v_mfma_f32_16x16x32_bf16 v[94:97], v[134:137], v[216:219], v[94:97]
	v_mfma_f32_16x16x32_bf16 v[90:93], v[142:145], v[216:219], v[90:93]
	v_mfma_f32_16x16x32_bf16 v[78:81], v[134:137], v[224:227], v[78:81]
	v_mfma_f32_16x16x32_bf16 v[74:77], v[142:145], v[224:227], v[74:77]
	v_mfma_f32_16x16x32_bf16 v[118:121], v[146:149], v[196:199], v[118:121]
	v_mfma_f32_16x16x32_bf16 v[114:117], v[166:169], v[196:199], v[114:117]
	v_mfma_f32_16x16x32_bf16 v[102:105], v[146:149], v[204:207], v[102:105]
	v_mfma_f32_16x16x32_bf16 v[98:101], v[166:169], v[204:207], v[98:101]
	v_mfma_f32_16x16x32_bf16 v[86:89], v[146:149], v[212:215], v[86:89]
	v_mfma_f32_16x16x32_bf16 v[82:85], v[166:169], v[212:215], v[82:85]
	v_mfma_f32_16x16x32_bf16 v[70:73], v[146:149], v[220:223], v[70:73]
	v_mfma_f32_16x16x32_bf16 v[66:69], v[166:169], v[220:223], v[66:69]
	v_mfma_f32_16x16x32_bf16 v[118:121], v[162:165], v[200:203], v[118:121]
	v_mfma_f32_16x16x32_bf16 v[114:117], v[192:195], v[200:203], v[114:117]
	v_mfma_f32_16x16x32_bf16 v[102:105], v[162:165], v[208:211], v[102:105]
	v_mfma_f32_16x16x32_bf16 v[98:101], v[192:195], v[208:211], v[98:101]
	v_mfma_f32_16x16x32_bf16 v[86:89], v[162:165], v[216:219], v[86:89]
	v_mfma_f32_16x16x32_bf16 v[82:85], v[192:195], v[216:219], v[82:85]
	v_mfma_f32_16x16x32_bf16 v[70:73], v[162:165], v[224:227], v[70:73]
	v_mfma_f32_16x16x32_bf16 v[66:69], v[192:195], v[224:227], v[66:69]
	s_barrier
	s_add_i32 s10, s40, s74
	v_lshl_add_u64 v[170:171], v[170:171], 0, s[56:57]
	s_mov_b32 m0, s10
	ds_read_b128 v[196:199], v191 offset:49152
	ds_read_b128 v[200:203], v191 offset:50176
	ds_read_b128 v[204:207], v191 offset:51200
	ds_read_b128 v[208:211], v191 offset:52224
	ds_read_b128 v[212:215], v191 offset:53248
	ds_read_b128 v[216:219], v191 offset:54272
	ds_read_b128 v[220:223], v191 offset:55296
	ds_read_b128 v[224:227], v191 offset:56320
	global_load_lds_dwordx4 v[170:171], off
	v_lshl_add_u64 v[170:171], v[228:229], 0, s[56:57]
	s_add_i32 m0, s10, 0x2000
	s_add_i32 s10, s41, s74
	global_load_lds_dwordx4 v[170:171], off
	v_lshl_add_u64 v[170:171], v[230:231], 0, s[56:57]
	s_mov_b32 m0, s10
	s_nop 0
	global_load_lds_dwordx4 v[170:171], off
	v_lshl_add_u64 v[170:171], v[232:233], 0, s[56:57]
	s_add_i32 m0, s10, 0x2000
	s_nop 0
	global_load_lds_dwordx4 v[170:171], off
	v_lshl_add_u64 v[170:171], v[234:235], 0, s[56:57]
	s_mov_b32 m0, s26
	s_nop 0
	global_load_lds_dwordx4 v[170:171], off
	v_lshl_add_u64 v[170:171], v[236:237], 0, s[56:57]
	s_mov_b32 m0, s27
	s_nop 0
	global_load_lds_dwordx4 v[170:171], off
	s_waitcnt vmcnt(8)
	s_waitcnt lgkmcnt(0)
	s_barrier
	v_mfma_f32_16x16x32_bf16 v[62:65], v[130:133], v[196:199], v[62:65]
	v_mfma_f32_16x16x32_bf16 v[58:61], v[138:141], v[196:199], v[58:61]
	v_mfma_f32_16x16x32_bf16 v[46:49], v[130:133], v[204:207], v[46:49]
	v_mfma_f32_16x16x32_bf16 v[42:45], v[138:141], v[204:207], v[42:45]
	v_mfma_f32_16x16x32_bf16 v[30:33], v[130:133], v[212:215], v[30:33]
	v_mfma_f32_16x16x32_bf16 v[26:29], v[138:141], v[212:215], v[26:29]
	v_mfma_f32_16x16x32_bf16 v[14:17], v[130:133], v[220:223], v[14:17]
	v_mfma_f32_16x16x32_bf16 v[10:13], v[138:141], v[220:223], v[10:13]
	v_mfma_f32_16x16x32_bf16 v[62:65], v[134:137], v[200:203], v[62:65]
	v_mfma_f32_16x16x32_bf16 v[58:61], v[142:145], v[200:203], v[58:61]
	v_mfma_f32_16x16x32_bf16 v[46:49], v[134:137], v[208:211], v[46:49]
	v_mfma_f32_16x16x32_bf16 v[42:45], v[142:145], v[208:211], v[42:45]
	v_mfma_f32_16x16x32_bf16 v[30:33], v[134:137], v[216:219], v[30:33]
	v_mfma_f32_16x16x32_bf16 v[26:29], v[142:145], v[216:219], v[26:29]
	v_mfma_f32_16x16x32_bf16 v[14:17], v[134:137], v[224:227], v[14:17]
	v_mfma_f32_16x16x32_bf16 v[10:13], v[142:145], v[224:227], v[10:13]
	v_mfma_f32_16x16x32_bf16 v[54:57], v[146:149], v[196:199], v[54:57]
	v_mfma_f32_16x16x32_bf16 v[50:53], v[166:169], v[196:199], v[50:53]
	v_mfma_f32_16x16x32_bf16 v[38:41], v[146:149], v[204:207], v[38:41]
	v_mfma_f32_16x16x32_bf16 v[34:37], v[166:169], v[204:207], v[34:37]
	v_mfma_f32_16x16x32_bf16 v[22:25], v[146:149], v[212:215], v[22:25]
	v_mfma_f32_16x16x32_bf16 v[18:21], v[166:169], v[212:215], v[18:21]
	v_mfma_f32_16x16x32_bf16 v[6:9], v[146:149], v[220:223], v[6:9]
	v_mfma_f32_16x16x32_bf16 v[2:5], v[166:169], v[220:223], v[2:5]
	v_mfma_f32_16x16x32_bf16 v[54:57], v[162:165], v[200:203], v[54:57]
	v_mfma_f32_16x16x32_bf16 v[50:53], v[192:195], v[200:203], v[50:53]
	v_mfma_f32_16x16x32_bf16 v[38:41], v[162:165], v[208:211], v[38:41]
	v_mfma_f32_16x16x32_bf16 v[34:37], v[192:195], v[208:211], v[34:37]
	v_mfma_f32_16x16x32_bf16 v[22:25], v[162:165], v[216:219], v[22:25]
	v_mfma_f32_16x16x32_bf16 v[18:21], v[192:195], v[216:219], v[18:21]
	v_mfma_f32_16x16x32_bf16 v[6:9], v[162:165], v[224:227], v[6:9]
	v_mfma_f32_16x16x32_bf16 v[2:5], v[192:195], v[224:227], v[2:5]
	s_barrier
	s_add_u32 s8, s8, 0x100
	s_addc_u32 s9, s9, 0
	s_add_u32 s36, s36, 0x100
	s_addc_u32 s38, s38, 0
	s_cmp_ge_u32 s39, s34
	s_mov_b32 s10, s39
	s_cbranch_scc0 .LBB0_110
	s_and_b64 vcc, exec, s[28:29]
	s_cbranch_vccz .LBB0_113
	s_barrier
